# v019 with up-GEMM stagger spread over 32 classes (blockIdx&31) x s_sleep 7 instead of 8 XCD classes x s_sleep 32
# baseline (speedup 1.0000x reference)
; __global__ void __launch_bounds__(512, 2) mega(Args a) {
;     ...
;                 if (st == 1) {
;                     pg8::Gemm g{xb, (const bf16_t*)(ws + WS_WUP + (size_t)L * 32 * MiB), M, FF, D}; pg8::StaticOrder S; S.init(M, FF, G, (int)blockIdx.x);
;                     pg8::EpiUp E{hid, ss + (size_t)(2 * L + 1) * M, FF};
;     ...
;                     for (int rep_ = 0; rep_ < REP_GUP; ++rep_) pg8::gemm_phase<pg8::EpiUp, pg8::StaticOrder, PG8_ALIGN, PG8_SP2>(lds, g, S, E);
.LBB0_1483:
	s_andn2_b64 vcc, exec, s[0:1]
	s_cbranch_vccnz .LBB0_1504
	v_readlane_b32 s0, v249, 33
	s_waitcnt vmcnt(0)
	v_mov_b32_e32 v8, v171
	v_readlane_b32 s1, v249, 34
	s_andn2_b64 vcc, exec, s[0:1]
	v_readfirstlane_b32 s0, v8
	s_cbranch_vccnz .LBB0_1504
	s_and_b32 s98, s2, 31
	s_cmp_eq_u32 s98, 0
	s_cbranch_scc1 .Lstag_up_done
.Lstag_up_loop:
	s_sleep 7
	s_sub_u32 s98, s98, 1
	s_cmp_lg_u32 s98, 0
	s_cbranch_scc1 .Lstag_up_loop
